# PG1 + mixer unit map: workgroups 0-31 (which also run the 32 sample units, the 5th round) get their batch's prompt chunks 0-3 incl. the two short-window chunks; the other 896 prompt units go to workgr
# speedup vs baseline: 1.0090x; 1.0090x over previous
; __device__ __forceinline__ void mixer_unit(const Params& p, int layer, int cu, LAS unsigned char* L, int wv) {
;     ...
;     const bool is_s = cu >= 1024;
;     const int b = is_s ? cu - 1024 : (cu >> 5), c = is_s ? 0 : (cu & 31);
;     const int tok0 = is_s ? MP + b * 64 : b * SEQ + c * 64;
; __global__ void __launch_bounds__(512, 2) hymba_fwd(Params p) {
;     ...
;         for (int cu = c; cu < 1056; cu += G) { int Gl = G; asm volatile("" : "+s"(Gl)); const int un = (Gl == 256 && cu < 1024) ? ((cu & 255) << 2) + (cu >> 8) : cu; mixer_unit(p, layer, un, L, wv); }
.LBB0_1319:
	s_mov_b32 s4, s20
	s_cmpk_eq_i32 s4, 0x100
	s_cselect_b64 s[4:5], -1, 0
	s_cmpk_lt_i32 s65, 0x400
	s_cselect_b64 s[6:7], -1, 0
	s_and_b64 s[4:5], s[6:7], s[4:5]
	s_and_b32 s6, s65, 0xff
	s_ashr_i32 s7, s65, 8
	s_cmpk_lt_i32 s6, 32
	s_cbranch_scc1 .Lmix_small
	s_sub_i32 s6, s6, 32
	s_lshl_b32 s6, s6, 2
	s_add_i32 s6, s6, s7
	s_mul_i32 s7, s6, 0x925
	s_lshr_b32 s7, s7, 16
	s_mul_i32 s16, s7, 28
	s_sub_i32 s6, s6, s16
	s_add_i32 s6, s6, 4
	s_lshl_b32 s7, s7, 5
	s_add_i32 s6, s6, s7
	s_branch .Lmix_join
.Lmix_small:
	s_lshl_b32 s6, s6, 5
	s_add_i32 s6, s6, s7
.Lmix_join:
	s_and_b64 s[4:5], s[4:5], exec
	s_cselect_b32 s16, s6, s65
	s_cmpk_gt_i32 s16, 0x3ff
	s_cselect_b64 s[4:5], -1, 0
	s_cmpk_lt_i32 s16, 0x400
	v_mov_b32_e32 v178, v183
	s_cselect_b64 s[40:41], -1, 0
	s_min_i32 s6, s16, 0x400
	s_ashr_i32 s18, s16, 5
	v_readfirstlane_b32 s66, v178
	s_and_b32 s76, s6, 31
	s_mov_b64 s[6:7], -1
	s_and_b64 vcc, exec, s[40:41]
	s_cbranch_vccz .LBB0_1321
	s_lshl_b32 s6, s18, 11
	s_lshl_b32 s29, s76, 6
	s_or_b32 s67, s29, s6
	s_mov_b64 s[6:7], 0
